# attention: exp/cvt of softmax interleaved with PV MFMAs (P fragment by fragment), waves 4-7 defer softmax+PV by one tile
# baseline (speedup 1.0000x reference)
; template <int DQK, bool CAUSAL, bool ROPE> ...
;     ...
;         if (grp == 1 && j > 0) AT_PV(j - 1, vprev);
.LBB0_885:
	s_cmp_eq_u32 s92, 0
	s_cselect_b64 s[4:5], -1, 0
	s_or_b64 s[4:5], s[86:87], s[4:5]
	s_sub_i32 s6, s92, 64
	s_cmp_gt_i32 s6, s64
	s_cselect_b64 s[6:7], -1, 0
	s_or_b64 s[4:5], s[4:5], s[6:7]
	s_and_b64 vcc, exec, s[4:5]
	s_cbranch_vccnz .LBB0_893
	s_mulk_i32 s0, 0x4800
	v_add_u32_e32 v17, s0, v244
	s_nop 8
	v_max3_f32 v2, v98, v99, v100
	v_max3_f32 v4, v101, v102, v103
	v_max3_f32 v5, v104, v105, v106
	v_max3_f32 v6, v107, v108, v109
	v_max3_f32 v2, v2, v110, v111
	v_max3_f32 v4, v4, v112, v113
	v_max3_f32 v5, v5, v82, v83
	v_max3_f32 v6, v6, v84, v85
	v_max3_f32 v2, v2, v86, v87
	v_max3_f32 v4, v4, v88, v89
	v_max3_f32 v5, v5, v90, v91
	v_max3_f32 v6, v6, v92, v93
	v_max3_f32 v2, v2, v94, v95
	v_max3_f32 v4, v4, v96, v97
	v_max3_f32 v2, v2, v4, v5
	v_max_f32_e32 v2, v2, v6
	v_mov_b32_e32 v4, v2
	s_nop 1
	v_permlane32_swap_b32_e32 v2, v4
	v_max_f32_e32 v2, v2, v4
	v_sub_f32_e32 v4, v2, v252
	v_mul_f32_e32 v4, 0x3dd53b94, v4
	s_mov_b32 s0, 0x41380000
	v_cmp_ge_f32_e32 vcc, s0, v4
	s_cmp_eq_u64 vcc, exec
	s_cbranch_scc1 .Ld2_exp
	v_max_f32_e32 v2, v2, v2
	v_max_f32_e32 v4, v252, v252
	v_max_f32_e32 v4, v4, v2
	v_sub_f32_e32 v2, v252, v4
	v_mul_f32_e32 v2, 0x3dd53b94, v2
	v_exp_f32_e32 v2, v2
	v_mov_b32_e32 v252, v4
	v_pk_mul_f32 v[80:81], v[80:81], v[2:3] op_sel_hi:[1,0]
	v_pk_mul_f32 v[78:79], v[78:79], v[2:3] op_sel_hi:[1,0]
	v_pk_mul_f32 v[76:77], v[76:77], v[2:3] op_sel_hi:[1,0]
	v_pk_mul_f32 v[74:75], v[74:75], v[2:3] op_sel_hi:[1,0]
	v_pk_mul_f32 v[72:73], v[72:73], v[2:3] op_sel_hi:[1,0]
	v_pk_mul_f32 v[70:71], v[70:71], v[2:3] op_sel_hi:[1,0]
	v_pk_mul_f32 v[68:69], v[68:69], v[2:3] op_sel_hi:[1,0]
	v_pk_mul_f32 v[66:67], v[66:67], v[2:3] op_sel_hi:[1,0]
	v_pk_mul_f32 v[64:65], v[64:65], v[2:3] op_sel_hi:[1,0]
	v_pk_mul_f32 v[62:63], v[62:63], v[2:3] op_sel_hi:[1,0]
	v_pk_mul_f32 v[60:61], v[60:61], v[2:3] op_sel_hi:[1,0]
	v_pk_mul_f32 v[58:59], v[58:59], v[2:3] op_sel_hi:[1,0]
	v_pk_mul_f32 v[56:57], v[56:57], v[2:3] op_sel_hi:[1,0]
	v_pk_mul_f32 v[54:55], v[54:55], v[2:3] op_sel_hi:[1,0]
	v_pk_mul_f32 v[52:53], v[52:53], v[2:3] op_sel_hi:[1,0]
	v_pk_mul_f32 v[50:51], v[50:51], v[2:3] op_sel_hi:[1,0]
	v_pk_mul_f32 v[48:49], v[48:49], v[2:3] op_sel_hi:[1,0]
	v_pk_mul_f32 v[46:47], v[46:47], v[2:3] op_sel_hi:[1,0]
	v_pk_mul_f32 v[44:45], v[44:45], v[2:3] op_sel_hi:[1,0]
	v_pk_mul_f32 v[42:43], v[42:43], v[2:3] op_sel_hi:[1,0]
	v_pk_mul_f32 v[40:41], v[40:41], v[2:3] op_sel_hi:[1,0]
	v_pk_mul_f32 v[38:39], v[38:39], v[2:3] op_sel_hi:[1,0]
	v_pk_mul_f32 v[36:37], v[36:37], v[2:3] op_sel_hi:[1,0]
	v_pk_mul_f32 v[34:35], v[34:35], v[2:3] op_sel_hi:[1,0]
	v_pk_mul_f32 v[32:33], v[32:33], v[2:3] op_sel_hi:[1,0]
	v_pk_mul_f32 v[30:31], v[30:31], v[2:3] op_sel_hi:[1,0]
	v_pk_mul_f32 v[28:29], v[28:29], v[2:3] op_sel_hi:[1,0]
	v_pk_mul_f32 v[26:27], v[26:27], v[2:3] op_sel_hi:[1,0]
	v_pk_mul_f32 v[24:25], v[24:25], v[2:3] op_sel_hi:[1,0]
	v_pk_mul_f32 v[22:23], v[22:23], v[2:3] op_sel_hi:[1,0]
	v_pk_mul_f32 v[20:21], v[20:21], v[2:3] op_sel_hi:[1,0]
	v_pk_mul_f32 v[18:19], v[18:19], v[2:3] op_sel_hi:[1,0]
	v_mul_f32_e32 v250, v250, v2
.Ld2_exp:
	v_mul_f32_e32 v2, 0xbdd53b94, v252
	ds_read_b128 v[4:7], v17 offset:51200
	ds_read_b128 v[8:11], v17 offset:55808
	ds_read_b128 v[12:15], v17 offset:60416
	ds_read_b128 v[176:179], v17 offset:65024
	v_fmamk_f32 v98, v98, 0x3dd53b94, v2
	v_fmamk_f32 v99, v99, 0x3dd53b94, v2
	v_fmamk_f32 v100, v100, 0x3dd53b94, v2
	v_fmamk_f32 v101, v101, 0x3dd53b94, v2
	v_fmamk_f32 v102, v102, 0x3dd53b94, v2
	v_fmamk_f32 v103, v103, 0x3dd53b94, v2
	v_fmamk_f32 v104, v104, 0x3dd53b94, v2
	v_fmamk_f32 v105, v105, 0x3dd53b94, v2
	v_exp_f32_e32 v98, v98
	v_exp_f32_e32 v99, v99
	v_exp_f32_e32 v100, v100
	v_exp_f32_e32 v101, v101
	v_exp_f32_e32 v102, v102
	v_exp_f32_e32 v103, v103
	v_exp_f32_e32 v104, v104
	v_exp_f32_e32 v105, v105
	v_add_f32_e32 v16, v98, v99
	v_add_f32_e32 v16, v16, v100
	v_add_f32_e32 v16, v16, v101
	v_add_f32_e32 v16, v16, v102
	v_add_f32_e32 v16, v16, v103
	v_add_f32_e32 v16, v16, v104
	v_add_f32_e32 v16, v16, v105
	v_cvt_pk_bf16_f32 v98, v98, v99
	v_cvt_pk_bf16_f32 v99, v100, v101
	v_cvt_pk_bf16_f32 v100, v102, v103
	v_cvt_pk_bf16_f32 v101, v104, v105
	v_fmamk_f32 v106, v106, 0x3dd53b94, v2
	s_waitcnt lgkmcnt(3)
	v_mfma_f32_32x32x16_bf16 v[66:81], v[4:7], v[98:101], v[66:81]
	ds_read_b128 v[4:7], v17 offset:51232
	v_fmamk_f32 v107, v107, 0x3dd53b94, v2
	v_fmamk_f32 v108, v108, 0x3dd53b94, v2
	v_fmamk_f32 v109, v109, 0x3dd53b94, v2
	v_fmamk_f32 v110, v110, 0x3dd53b94, v2
	v_fmamk_f32 v111, v111, 0x3dd53b94, v2
	v_fmamk_f32 v112, v112, 0x3dd53b94, v2
	s_waitcnt lgkmcnt(3)
	v_mfma_f32_32x32x16_bf16 v[50:65], v[8:11], v[98:101], v[50:65]
	ds_read_b128 v[8:11], v17 offset:55840
	v_fmamk_f32 v113, v113, 0x3dd53b94, v2
	v_exp_f32_e32 v106, v106
	v_exp_f32_e32 v107, v107
	v_exp_f32_e32 v108, v108
	v_exp_f32_e32 v109, v109
	v_exp_f32_e32 v110, v110
	s_waitcnt lgkmcnt(3)
	v_mfma_f32_32x32x16_bf16 v[34:49], v[12:15], v[98:101], v[34:49]
	ds_read_b128 v[12:15], v17 offset:60448
	v_exp_f32_e32 v111, v111
	v_exp_f32_e32 v112, v112
	v_exp_f32_e32 v113, v113
	v_pk_add_f32 v[102:103], v[106:107], v[108:109]
	v_pk_add_f32 v[104:105], v[110:111], v[112:113]
	s_waitcnt lgkmcnt(3)
	v_mfma_f32_32x32x16_bf16 v[18:33], v[176:179], v[98:101], v[18:33]
	ds_read_b128 v[176:179], v17 offset:65056
	v_pk_add_f32 v[102:103], v[102:103], v[104:105]
	v_cvt_pk_bf16_f32 v106, v106, v107
	v_cvt_pk_bf16_f32 v107, v108, v109
	v_cvt_pk_bf16_f32 v108, v110, v111
	v_cvt_pk_bf16_f32 v109, v112, v113
	v_fmamk_f32 v82, v82, 0x3dd53b94, v2
	s_waitcnt lgkmcnt(3)
	v_mfma_f32_32x32x16_bf16 v[66:81], v[4:7], v[106:109], v[66:81]
	ds_read_b128 v[4:7], v17 offset:51264
	v_fmamk_f32 v83, v83, 0x3dd53b94, v2
	v_fmamk_f32 v84, v84, 0x3dd53b94, v2
	v_fmamk_f32 v85, v85, 0x3dd53b94, v2
	v_fmamk_f32 v86, v86, 0x3dd53b94, v2
	v_fmamk_f32 v87, v87, 0x3dd53b94, v2
	v_fmamk_f32 v88, v88, 0x3dd53b94, v2
	s_waitcnt lgkmcnt(3)
	v_mfma_f32_32x32x16_bf16 v[50:65], v[8:11], v[106:109], v[50:65]
	ds_read_b128 v[8:11], v17 offset:55872
	v_fmamk_f32 v89, v89, 0x3dd53b94, v2
	v_exp_f32_e32 v82, v82
	v_exp_f32_e32 v83, v83
	v_exp_f32_e32 v84, v84
	v_exp_f32_e32 v85, v85
	v_exp_f32_e32 v86, v86
	s_waitcnt lgkmcnt(3)
	v_mfma_f32_32x32x16_bf16 v[34:49], v[12:15], v[106:109], v[34:49]
	ds_read_b128 v[12:15], v17 offset:60480
	v_exp_f32_e32 v87, v87
	v_exp_f32_e32 v88, v88
	v_exp_f32_e32 v89, v89
	v_pk_add_f32 v[104:105], v[82:83], v[84:85]
	v_pk_add_f32 v[102:103], v[102:103], v[104:105]
	v_pk_add_f32 v[104:105], v[86:87], v[88:89]
	s_waitcnt lgkmcnt(3)
	v_mfma_f32_32x32x16_bf16 v[18:33], v[176:179], v[106:109], v[18:33]
	ds_read_b128 v[176:179], v17 offset:65088
	v_pk_add_f32 v[102:103], v[102:103], v[104:105]
	v_cvt_pk_bf16_f32 v82, v82, v83
	v_cvt_pk_bf16_f32 v83, v84, v85
	v_cvt_pk_bf16_f32 v84, v86, v87
	v_cvt_pk_bf16_f32 v85, v88, v89
	v_fmamk_f32 v90, v90, 0x3dd53b94, v2
	s_waitcnt lgkmcnt(3)
	v_mfma_f32_32x32x16_bf16 v[66:81], v[4:7], v[82:85], v[66:81]
	ds_read_b128 v[4:7], v17 offset:51296
	v_fmamk_f32 v91, v91, 0x3dd53b94, v2
	v_fmamk_f32 v92, v92, 0x3dd53b94, v2
	v_fmamk_f32 v93, v93, 0x3dd53b94, v2
	v_fmamk_f32 v94, v94, 0x3dd53b94, v2
	v_fmamk_f32 v95, v95, 0x3dd53b94, v2
	v_fmamk_f32 v96, v96, 0x3dd53b94, v2
	s_waitcnt lgkmcnt(3)
	v_mfma_f32_32x32x16_bf16 v[50:65], v[8:11], v[82:85], v[50:65]
	ds_read_b128 v[8:11], v17 offset:55904
	v_fmamk_f32 v97, v97, 0x3dd53b94, v2
	v_exp_f32_e32 v90, v90
	v_exp_f32_e32 v91, v91
	v_exp_f32_e32 v92, v92
	v_exp_f32_e32 v93, v93
	v_exp_f32_e32 v94, v94
	s_waitcnt lgkmcnt(3)
	v_mfma_f32_32x32x16_bf16 v[34:49], v[12:15], v[82:85], v[34:49]
	ds_read_b128 v[12:15], v17 offset:60512
	v_exp_f32_e32 v95, v95
	v_exp_f32_e32 v96, v96
	v_exp_f32_e32 v97, v97
	v_pk_add_f32 v[104:105], v[90:91], v[92:93]
	v_pk_add_f32 v[102:103], v[102:103], v[104:105]
	v_pk_add_f32 v[104:105], v[94:95], v[96:97]
	s_waitcnt lgkmcnt(3)
	v_mfma_f32_32x32x16_bf16 v[18:33], v[176:179], v[82:85], v[18:33]
	ds_read_b128 v[176:179], v17 offset:65120
	v_pk_add_f32 v[102:103], v[102:103], v[104:105]
	v_cvt_pk_bf16_f32 v90, v90, v91
	v_cvt_pk_bf16_f32 v91, v92, v93
	v_cvt_pk_bf16_f32 v92, v94, v95
	v_cvt_pk_bf16_f32 v93, v96, v97
	s_nop 0
	s_waitcnt lgkmcnt(3)
	v_mfma_f32_32x32x16_bf16 v[66:81], v[4:7], v[90:93], v[66:81]
	v_add_f32_e32 v16, v16, v102
	s_waitcnt lgkmcnt(2)
	v_mfma_f32_32x32x16_bf16 v[50:65], v[8:11], v[90:93], v[50:65]
	v_add_f32_e32 v16, v16, v103
	s_waitcnt lgkmcnt(1)
	v_mfma_f32_32x32x16_bf16 v[34:49], v[12:15], v[90:93], v[34:49]
	v_add_f32_e32 v250, v250, v16
	s_waitcnt lgkmcnt(0)
	v_mfma_f32_32x32x16_bf16 v[18:33], v[176:179], v[90:93], v[18:33]
	s_branch .LBB0_893
.LBB0_887:
	s_or_b64 s[0:1], s[84:85], s[68:69]
	s_and_b64 vcc, exec, s[0:1]
	s_cbranch_vccnz .LBB0_889
.LBB0_889:
	s_add_i32 s0, s71, 1
	s_cmp_lg_u32 s71, 2
	s_cselect_b32 s1, s0, 0
	s_andn2_b64 vcc, exec, s[66:67]
	s_cbranch_vccnz .LBB0_891
	s_bitcmp1_b32 s2, 0
	s_cselect_b32 s0, 0x6400, 0
	s_add_i32 s0, s0, 0
	v_add_u32_e32 v2, s0, v235
	v_add_u32_e32 v4, v2, v238
	v_add_u32_e32 v2, v2, v239
	s_waitcnt vmcnt(4)
	ds_write_b128 v4, v[114:117]
	s_waitcnt vmcnt(3)
	ds_write_b128 v2, v[122:125]
	s_mul_i32 s4, s1, 0x4800
	v_add3_u32 v2, s0, v240, v236
	s_waitcnt vmcnt(2)
	ds_write_b128 v2, v[146:149] offset:256
	v_add_u32_e32 v2, s4, v241
	v_add_u32_e32 v4, v2, v242
	v_add_u32_e32 v2, v2, v243
	s_waitcnt vmcnt(1)
	ds_write_b128 v4, v[158:161] offset:51200
	s_waitcnt vmcnt(0)
	ds_write_b128 v2, v[162:165] offset:51200

.LBB0_896:
	s_and_b64 vcc, exec, s[84:85]
	s_cbranch_vccnz .LBB0_889
	s_mul_i32 s0, s71, 0x4800
	v_add_u32_e32 v17, s0, v244
	s_nop 8
	v_max3_f32 v2, v98, v99, v100
	v_max3_f32 v4, v101, v102, v103
	v_max3_f32 v5, v104, v105, v106
	v_max3_f32 v6, v107, v108, v109
	v_max3_f32 v2, v2, v110, v111
	v_max3_f32 v4, v4, v112, v113
	v_max3_f32 v5, v5, v82, v83
	v_max3_f32 v6, v6, v84, v85
	v_max3_f32 v2, v2, v86, v87
	v_max3_f32 v4, v4, v88, v89
	v_max3_f32 v5, v5, v90, v91
	v_max3_f32 v6, v6, v92, v93
	v_max3_f32 v2, v2, v94, v95
	v_max3_f32 v4, v4, v96, v97
	v_max3_f32 v2, v2, v4, v5
	v_max_f32_e32 v2, v2, v6
	v_mov_b32_e32 v4, v2
	s_nop 1
	v_permlane32_swap_b32_e32 v2, v4
	v_max_f32_e32 v2, v2, v4
	v_sub_f32_e32 v4, v2, v252
	v_mul_f32_e32 v4, 0x3dd53b94, v4
	s_mov_b32 s0, 0x41380000
	v_cmp_ge_f32_e32 vcc, s0, v4
	s_cmp_eq_u64 vcc, exec
	s_cbranch_scc1 .Ld1_exp
	v_max_f32_e32 v2, v2, v2
	v_max_f32_e32 v4, v252, v252
	v_max_f32_e32 v4, v4, v2
	v_sub_f32_e32 v2, v252, v4
	v_mul_f32_e32 v2, 0x3dd53b94, v2
	v_exp_f32_e32 v2, v2
	v_mov_b32_e32 v252, v4
	v_pk_mul_f32 v[80:81], v[80:81], v[2:3] op_sel_hi:[1,0]
	v_pk_mul_f32 v[78:79], v[78:79], v[2:3] op_sel_hi:[1,0]
	v_pk_mul_f32 v[76:77], v[76:77], v[2:3] op_sel_hi:[1,0]
	v_pk_mul_f32 v[74:75], v[74:75], v[2:3] op_sel_hi:[1,0]
	v_pk_mul_f32 v[72:73], v[72:73], v[2:3] op_sel_hi:[1,0]
	v_pk_mul_f32 v[70:71], v[70:71], v[2:3] op_sel_hi:[1,0]
	v_pk_mul_f32 v[68:69], v[68:69], v[2:3] op_sel_hi:[1,0]
	v_pk_mul_f32 v[66:67], v[66:67], v[2:3] op_sel_hi:[1,0]
	v_pk_mul_f32 v[64:65], v[64:65], v[2:3] op_sel_hi:[1,0]
	v_pk_mul_f32 v[62:63], v[62:63], v[2:3] op_sel_hi:[1,0]
	v_pk_mul_f32 v[60:61], v[60:61], v[2:3] op_sel_hi:[1,0]
	v_pk_mul_f32 v[58:59], v[58:59], v[2:3] op_sel_hi:[1,0]
	v_pk_mul_f32 v[56:57], v[56:57], v[2:3] op_sel_hi:[1,0]
	v_pk_mul_f32 v[54:55], v[54:55], v[2:3] op_sel_hi:[1,0]
	v_pk_mul_f32 v[52:53], v[52:53], v[2:3] op_sel_hi:[1,0]
	v_pk_mul_f32 v[50:51], v[50:51], v[2:3] op_sel_hi:[1,0]
	v_pk_mul_f32 v[48:49], v[48:49], v[2:3] op_sel_hi:[1,0]
	v_pk_mul_f32 v[46:47], v[46:47], v[2:3] op_sel_hi:[1,0]
	v_pk_mul_f32 v[44:45], v[44:45], v[2:3] op_sel_hi:[1,0]
	v_pk_mul_f32 v[42:43], v[42:43], v[2:3] op_sel_hi:[1,0]
	v_pk_mul_f32 v[40:41], v[40:41], v[2:3] op_sel_hi:[1,0]
	v_pk_mul_f32 v[38:39], v[38:39], v[2:3] op_sel_hi:[1,0]
	v_pk_mul_f32 v[36:37], v[36:37], v[2:3] op_sel_hi:[1,0]
	v_pk_mul_f32 v[34:35], v[34:35], v[2:3] op_sel_hi:[1,0]
	v_pk_mul_f32 v[32:33], v[32:33], v[2:3] op_sel_hi:[1,0]
	v_pk_mul_f32 v[30:31], v[30:31], v[2:3] op_sel_hi:[1,0]
	v_pk_mul_f32 v[28:29], v[28:29], v[2:3] op_sel_hi:[1,0]
	v_pk_mul_f32 v[26:27], v[26:27], v[2:3] op_sel_hi:[1,0]
	v_pk_mul_f32 v[24:25], v[24:25], v[2:3] op_sel_hi:[1,0]
	v_pk_mul_f32 v[22:23], v[22:23], v[2:3] op_sel_hi:[1,0]
	v_pk_mul_f32 v[20:21], v[20:21], v[2:3] op_sel_hi:[1,0]
	v_pk_mul_f32 v[18:19], v[18:19], v[2:3] op_sel_hi:[1,0]
	v_mul_f32_e32 v250, v250, v2

; template <int DQK, bool CAUSAL, bool ROPE> ...
;     ...
;     if (grp == 1) AT_PV(ntiles - 1, vprev);
.LBB0_899:
	s_and_b64 vcc, exec, s[88:89]
	s_cbranch_vccz .LBB0_881
	s_lshl_b32 s0, s33, 6
	s_sub_i32 s0, s0, 64
	s_cmp_gt_i32 s0, s64
	s_cbranch_scc1 .LBB0_881
	s_mul_i32 s0, s71, 0x4800
	v_add_u32_e32 v17, s0, v244
	s_nop 8
	v_max3_f32 v2, v98, v99, v100
	v_max3_f32 v4, v101, v102, v103
	v_max3_f32 v5, v104, v105, v106
	v_max3_f32 v6, v107, v108, v109
	v_max3_f32 v2, v2, v110, v111
	v_max3_f32 v4, v4, v112, v113
	v_max3_f32 v5, v5, v82, v83
	v_max3_f32 v6, v6, v84, v85
	v_max3_f32 v2, v2, v86, v87
	v_max3_f32 v4, v4, v88, v89
	v_max3_f32 v5, v5, v90, v91
	v_max3_f32 v6, v6, v92, v93
	v_max3_f32 v2, v2, v94, v95
	v_max3_f32 v4, v4, v96, v97
	v_max3_f32 v2, v2, v4, v5
	v_max_f32_e32 v2, v2, v6
	v_mov_b32_e32 v4, v2
	s_nop 1
	v_permlane32_swap_b32_e32 v2, v4
	v_max_f32_e32 v2, v2, v4
	v_sub_f32_e32 v4, v2, v252
	v_mul_f32_e32 v4, 0x3dd53b94, v4
	s_mov_b32 s0, 0x41380000
	v_cmp_ge_f32_e32 vcc, s0, v4
	s_cmp_eq_u64 vcc, exec
	s_cbranch_scc1 .Ld3_exp
	v_max_f32_e32 v2, v2, v2
	v_max_f32_e32 v4, v252, v252
	v_max_f32_e32 v4, v4, v2
	v_sub_f32_e32 v2, v252, v4
	v_mul_f32_e32 v2, 0x3dd53b94, v2
	v_exp_f32_e32 v2, v2
	v_mov_b32_e32 v252, v4
	v_pk_mul_f32 v[80:81], v[80:81], v[2:3] op_sel_hi:[1,0]
	v_pk_mul_f32 v[78:79], v[78:79], v[2:3] op_sel_hi:[1,0]
	v_pk_mul_f32 v[76:77], v[76:77], v[2:3] op_sel_hi:[1,0]
	v_pk_mul_f32 v[74:75], v[74:75], v[2:3] op_sel_hi:[1,0]
	v_pk_mul_f32 v[72:73], v[72:73], v[2:3] op_sel_hi:[1,0]
	v_pk_mul_f32 v[70:71], v[70:71], v[2:3] op_sel_hi:[1,0]
	v_pk_mul_f32 v[68:69], v[68:69], v[2:3] op_sel_hi:[1,0]
	v_pk_mul_f32 v[66:67], v[66:67], v[2:3] op_sel_hi:[1,0]
	v_pk_mul_f32 v[64:65], v[64:65], v[2:3] op_sel_hi:[1,0]
	v_pk_mul_f32 v[62:63], v[62:63], v[2:3] op_sel_hi:[1,0]
	v_pk_mul_f32 v[60:61], v[60:61], v[2:3] op_sel_hi:[1,0]
	v_pk_mul_f32 v[58:59], v[58:59], v[2:3] op_sel_hi:[1,0]
	v_pk_mul_f32 v[56:57], v[56:57], v[2:3] op_sel_hi:[1,0]
	v_pk_mul_f32 v[54:55], v[54:55], v[2:3] op_sel_hi:[1,0]
	v_pk_mul_f32 v[52:53], v[52:53], v[2:3] op_sel_hi:[1,0]
	v_pk_mul_f32 v[50:51], v[50:51], v[2:3] op_sel_hi:[1,0]
	v_pk_mul_f32 v[48:49], v[48:49], v[2:3] op_sel_hi:[1,0]
	v_pk_mul_f32 v[46:47], v[46:47], v[2:3] op_sel_hi:[1,0]
	v_pk_mul_f32 v[44:45], v[44:45], v[2:3] op_sel_hi:[1,0]
	v_pk_mul_f32 v[42:43], v[42:43], v[2:3] op_sel_hi:[1,0]
	v_pk_mul_f32 v[40:41], v[40:41], v[2:3] op_sel_hi:[1,0]
	v_pk_mul_f32 v[38:39], v[38:39], v[2:3] op_sel_hi:[1,0]
	v_pk_mul_f32 v[36:37], v[36:37], v[2:3] op_sel_hi:[1,0]
	v_pk_mul_f32 v[34:35], v[34:35], v[2:3] op_sel_hi:[1,0]
	v_pk_mul_f32 v[32:33], v[32:33], v[2:3] op_sel_hi:[1,0]
	v_pk_mul_f32 v[30:31], v[30:31], v[2:3] op_sel_hi:[1,0]
	v_pk_mul_f32 v[28:29], v[28:29], v[2:3] op_sel_hi:[1,0]
	v_pk_mul_f32 v[26:27], v[26:27], v[2:3] op_sel_hi:[1,0]
	v_pk_mul_f32 v[24:25], v[24:25], v[2:3] op_sel_hi:[1,0]
	v_pk_mul_f32 v[22:23], v[22:23], v[2:3] op_sel_hi:[1,0]
	v_pk_mul_f32 v[20:21], v[20:21], v[2:3] op_sel_hi:[1,0]
	v_pk_mul_f32 v[18:19], v[18:19], v[2:3] op_sel_hi:[1,0]
	v_mul_f32_e32 v250, v250, v2
